# s_setprio 1 during the S-chain and first softmax phases of both attention loops, prio 0 in PV tail; rest unchanged
# speedup vs baseline: 1.0702x; 1.0117x over previous
; template <int DK>
; DEVI void attn_tile(const char* kb, const char* vb, const bool first, const bf16x8 (&qf)[2][DK / 32], f32x4 (&o)[2][4],
;                     float (&mrun)[2], float (&lsum)[2], const int l15, const int quad) {
;     ...
; #pragma unroll
;   for (int ks = 0; ks < 4; ++ks)
; #pragma unroll
;     for (int kk = 0; kk < NKK; ++kk) {
;       bf16x8 kf = *reinterpret_cast<const bf16x8*>(kb + (ks * 16 + l15) * KSTR + (kk * 32 + quad * 8) * 2);
;       s[0][ks] = mfma16(kf, qf[0][kk], s[0][ks]);
;       s[1][ks] = mfma16(kf, qf[1][kk], s[1][ks]);
;     }
;   bf16x8 pf[2][2];
; #pragma unroll
;   for (int qt = 0; qt < 2; ++qt) {
;     float mx = fmaxf(fmaxf(s[qt][0][0], s[qt][0][1]), fmaxf(s[qt][0][2], s[qt][0][3]));
; #pragma unroll
;     for (int ks = 1; ks < 4; ++ks) mx = fmaxf(mx, fmaxf(fmaxf(s[qt][ks][0], s[qt][ks][1]), fmaxf(s[qt][ks][2], s[qt][ks][3])));
;     if (__any(first || (mx > 8.f))) {
;       float rm = fmaxf(mx, __shfl_xor(mx, 16));
;       rm = fmaxf(rm, __shfl_xor(rm, 32));
;       const float delta = first ? rm : fmaxf(rm, 0.f);
;       const float alpha = first ? 1.f : ex2(-delta);
;       mrun[qt] += delta;
;       lsum[qt] *= alpha;
; #pragma unroll
;       for (int ks = 0; ks < 4; ++ks)
; #pragma unroll
;         for (int j = 0; j < 4; ++j) s[qt][ks][j] -= delta;
; #pragma unroll
;       for (int dd = 0; dd < 4; ++dd)
; #pragma unroll
;         for (int j = 0; j < 4; ++j) o[qt][dd][j] *= alpha;
;     }
;     float ps = 0.f;
; #pragma unroll
;     for (int ks = 0; ks < 4; ++ks)
; #pragma unroll
;       for (int j = 0; j < 4; ++j) { float pv = ex2(s[qt][ks][j]); s[qt][ks][j] = pv; ps += pv; }
;     lsum[qt] += ps;
; #pragma unroll
;     for (int k2 = 0; k2 < 2; ++k2) {
;       u32x4 wv;
;       wv[0] = pack2(s[qt][2 * k2][0], s[qt][2 * k2][1]);
;       wv[1] = pack2(s[qt][2 * k2][2], s[qt][2 * k2][3]);
;       wv[2] = pack2(s[qt][2 * k2 + 1][0], s[qt][2 * k2 + 1][1]);
;       wv[3] = pack2(s[qt][2 * k2 + 1][2], s[qt][2 * k2 + 1][3]);
;       pf[qt][k2] = as_bf8(wv);
;     }
;   }
; #pragma unroll
;   for (int dd = 0; dd < 4; ++dd)
; #pragma unroll
;     for (int k2 = 0; k2 < 2; ++k2) {
;       u32x2 lo = *reinterpret_cast<const u32x2*>(vb + (dd * 16 + l15) * 144 + (k2 * 32 + quad * 4) * 2);
;       u32x2 hi = *reinterpret_cast<const u32x2*>(vb + (dd * 16 + l15) * 144 + (k2 * 32 + 16 + quad * 4) * 2);
.Lgqa_loop_g:
	v_add_u32_e32 v211, s18, v168
	ds_read_b128 v[100:103], v211
	ds_read_b128 v[104:107], v211 offset:64
	global_load_dwordx4 v[192:195], v204, s[12:13]
	global_load_dwordx4 v[196:199], v205, s[12:13]
	global_load_dwordx4 v[244:247], v206, s[22:23]
	global_load_dwordx4 v[164:167], v207, s[22:23]
	s_add_i32 s96, s11, 2
	s_cmp_lt_i32 s96, s3
	s_cselect_b32 s96, 0x2000, 0
	s_cselect_b32 s17, 0x80, 0
	s_add_u32 s12, s12, s96
	s_addc_u32 s13, s13, 0
	s_add_u32 s22, s22, s17
	s_addc_u32 s23, s23, 0
	ds_read_b128 v[108:111], v211 offset:2560
	ds_read_b128 v[112:115], v211 offset:2624
	ds_read_b128 v[116:119], v211 offset:5120
	ds_read_b128 v[120:123], v211 offset:5184
	ds_read_b128 v[124:127], v211 offset:7680
	ds_read_b128 v[128:131], v211 offset:7744
	s_setprio 1
	s_waitcnt lgkmcnt(7)
	v_mfma_f32_16x16x32_bf16 v[132:135], v[100:103], v[4:7], v[228:231]
	s_waitcnt lgkmcnt(6)
	v_mfma_f32_16x16x32_bf16 v[132:135], v[104:107], v[12:15], v[132:135]
	s_waitcnt lgkmcnt(4)
	v_mfma_f32_16x16x32_bf16 v[136:139], v[108:111], v[4:7], v[228:231]
	v_mfma_f32_16x16x32_bf16 v[136:139], v[112:115], v[12:15], v[136:139]
	s_waitcnt lgkmcnt(2)
	v_mfma_f32_16x16x32_bf16 v[140:143], v[116:119], v[4:7], v[228:231]
	v_mfma_f32_16x16x32_bf16 v[140:143], v[120:123], v[12:15], v[140:143]
	s_waitcnt lgkmcnt(0)
	v_mfma_f32_16x16x32_bf16 v[144:147], v[124:127], v[4:7], v[228:231]
	v_mfma_f32_16x16x32_bf16 v[144:147], v[128:131], v[12:15], v[144:147]
	v_mfma_f32_16x16x32_bf16 v[212:215], v[100:103], v[8:11], v[236:239]
	v_mfma_f32_16x16x32_bf16 v[212:215], v[104:107], v[16:19], v[212:215]
	v_max3_f32 v153, v132, v133, v134
	v_max3_f32 v154, v135, v136, v137
	v_mfma_f32_16x16x32_bf16 v[216:219], v[108:111], v[8:11], v[236:239]
	v_max3_f32 v155, v138, v139, v140
	v_max3_f32 v156, v141, v142, v143
	v_mfma_f32_16x16x32_bf16 v[216:219], v[112:115], v[16:19], v[216:219]
	s_nop 0
	v_max3_f32 v153, v153, v154, v144
	v_max3_f32 v155, v155, v156, v145
	v_max3_f32 v153, v153, v155, v146
	v_max_f32_e32 v153, v153, v147
	v_cmp_lt_f32_e32 vcc, 0x41000000, v153
	s_cbranch_vccnz .Lgqa_rare0_ga
.Lgqa_join0_ga:
	v_add_u32_e32 v208, s18, v169
	ds_read_b64 v[100:101], v208 offset:0
	ds_read_b64 v[102:103], v208 offset:32
	ds_read_b64 v[104:105], v208 offset:2304
	ds_read_b64 v[106:107], v208 offset:2336
	ds_read_b64 v[108:109], v208 offset:4608
	ds_read_b64 v[110:111], v208 offset:4640
	ds_read_b64 v[112:113], v208 offset:6912
	ds_read_b64 v[114:115], v208 offset:6944
	v_mfma_f32_16x16x32_bf16 v[220:223], v[116:119], v[8:11], v[236:239]
	v_exp_f32_e32 v132, v132
	v_exp_f32_e32 v133, v133
	v_exp_f32_e32 v134, v134
	v_exp_f32_e32 v135, v135
	v_add_f32_e32 v154, v132, v133
	v_exp_f32_e32 v136, v136
	v_add_f32_e32 v155, v134, v135
	v_exp_f32_e32 v137, v137
	v_exp_f32_e32 v138, v138
	v_add_f32_e32 v154, v154, v136
	v_mfma_f32_16x16x32_bf16 v[220:223], v[120:123], v[16:19], v[220:223]
	v_exp_f32_e32 v139, v139
	v_add_f32_e32 v155, v155, v137
	v_exp_f32_e32 v140, v140
	v_add_f32_e32 v154, v154, v138
	v_exp_f32_e32 v141, v141
	v_add_f32_e32 v155, v155, v139
	v_exp_f32_e32 v142, v142
	v_add_f32_e32 v154, v154, v140
	v_exp_f32_e32 v143, v143
	v_add_f32_e32 v155, v155, v141
	v_mfma_f32_16x16x32_bf16 v[224:227], v[124:127], v[8:11], v[236:239]
	v_exp_f32_e32 v144, v144
	v_add_f32_e32 v154, v154, v142
	v_exp_f32_e32 v145, v145
	v_add_f32_e32 v155, v155, v143
	v_exp_f32_e32 v146, v146
	v_add_f32_e32 v154, v154, v144
	v_exp_f32_e32 v147, v147
	v_add_f32_e32 v155, v155, v145
	v_add_f32_e32 v154, v154, v146
	v_add_f32_e32 v155, v155, v147
	v_mfma_f32_16x16x32_bf16 v[224:227], v[128:131], v[16:19], v[224:227]
	v_add_f32_e32 v154, v154, v155
	v_add_f32_e32 v176, v176, v154
	v_cvt_pk_bf16_f32 v228, v132, v133
	v_cvt_pk_bf16_f32 v229, v134, v135
	v_cvt_pk_bf16_f32 v230, v136, v137
	v_cvt_pk_bf16_f32 v231, v138, v139
	v_cvt_pk_bf16_f32 v232, v140, v141
	v_cvt_pk_bf16_f32 v233, v142, v143
	v_cvt_pk_bf16_f32 v234, v144, v145
	v_cvt_pk_bf16_f32 v235, v146, v147
	ds_read_b64 v[116:117], v208 offset:64
	ds_read_b64 v[118:119], v208 offset:96
	ds_read_b64 v[120:121], v208 offset:2368
	ds_read_b64 v[122:123], v208 offset:2400
	ds_read_b64 v[124:125], v208 offset:4672
	ds_read_b64 v[126:127], v208 offset:4704
	ds_read_b64 v[128:129], v208 offset:6976
	ds_read_b64 v[130:131], v208 offset:7008
	v_max3_f32 v153, v212, v213, v214
	v_max3_f32 v154, v215, v216, v217
	v_max3_f32 v155, v218, v219, v220
	v_max3_f32 v156, v221, v222, v223
	s_setprio 0
	s_waitcnt lgkmcnt(12)
	v_mfma_f32_16x16x32_bf16 v[52:55], v[100:103], v[228:231], v[52:55]
	v_max3_f32 v153, v153, v154, v224
	v_max3_f32 v155, v155, v156, v225
	v_mfma_f32_16x16x32_bf16 v[56:59], v[104:107], v[228:231], v[56:59]
	v_max3_f32 v153, v153, v155, v226
	v_max_f32_e32 v153, v153, v227
	v_cmp_lt_f32_e32 vcc, 0x41000000, v153
	s_cbranch_vccnz .Lgqa_rare1_ga
; template <int DK>
; DEVI void attn_tile(const char* kb, const char* vb, const bool first, const bf16x8 (&qf)[2][DK / 32], f32x4 (&o)[2][4],
;                     float (&mrun)[2], float (&lsum)[2], const int l15, const int quad) {
;     ...
; #pragma unroll
;   for (int ks = 0; ks < 4; ++ks)
; #pragma unroll
;     for (int kk = 0; kk < NKK; ++kk) {
;       bf16x8 kf = *reinterpret_cast<const bf16x8*>(kb + (ks * 16 + l15) * KSTR + (kk * 32 + quad * 8) * 2);
;       s[0][ks] = mfma16(kf, qf[0][kk], s[0][ks]);
;       s[1][ks] = mfma16(kf, qf[1][kk], s[1][ks]);
;     }
;   bf16x8 pf[2][2];
; #pragma unroll
;   for (int qt = 0; qt < 2; ++qt) {
;     float mx = fmaxf(fmaxf(s[qt][0][0], s[qt][0][1]), fmaxf(s[qt][0][2], s[qt][0][3]));
; #pragma unroll
;     for (int ks = 1; ks < 4; ++ks) mx = fmaxf(mx, fmaxf(fmaxf(s[qt][ks][0], s[qt][ks][1]), fmaxf(s[qt][ks][2], s[qt][ks][3])));
;     if (__any(first || (mx > 8.f))) {
;       float rm = fmaxf(mx, __shfl_xor(mx, 16));
;       rm = fmaxf(rm, __shfl_xor(rm, 32));
;       const float delta = first ? rm : fmaxf(rm, 0.f);
;       const float alpha = first ? 1.f : ex2(-delta);
;       mrun[qt] += delta;
;       lsum[qt] *= alpha;
; #pragma unroll
;       for (int ks = 0; ks < 4; ++ks)
; #pragma unroll
;         for (int j = 0; j < 4; ++j) s[qt][ks][j] -= delta;
; #pragma unroll
;       for (int dd = 0; dd < 4; ++dd)
; #pragma unroll
;         for (int j = 0; j < 4; ++j) o[qt][dd][j] *= alpha;
;     }
;     float ps = 0.f;
; #pragma unroll
;     for (int ks = 0; ks < 4; ++ks)
; #pragma unroll
;       for (int j = 0; j < 4; ++j) { float pv = ex2(s[qt][ks][j]); s[qt][ks][j] = pv; ps += pv; }
;     lsum[qt] += ps;
; #pragma unroll
;     for (int k2 = 0; k2 < 2; ++k2) {
;       u32x4 wv;
;       wv[0] = pack2(s[qt][2 * k2][0], s[qt][2 * k2][1]);
;       wv[1] = pack2(s[qt][2 * k2][2], s[qt][2 * k2][3]);
;       wv[2] = pack2(s[qt][2 * k2 + 1][0], s[qt][2 * k2 + 1][1]);
;       wv[3] = pack2(s[qt][2 * k2 + 1][2], s[qt][2 * k2 + 1][3]);
;       pf[qt][k2] = as_bf8(wv);
;     }
;   }
; #pragma unroll
;   for (int dd = 0; dd < 4; ++dd)
; #pragma unroll
;     for (int k2 = 0; k2 < 2; ++k2) {
;       u32x2 lo = *reinterpret_cast<const u32x2*>(vb + (dd * 16 + l15) * 144 + (k2 * 32 + quad * 4) * 2);
;       u32x2 hi = *reinterpret_cast<const u32x2*>(vb + (dd * 16 + l15) * 144 + (k2 * 32 + 16 + quad * 4) * 2);
.Lgqa_join1_ga:
	s_waitcnt lgkmcnt(8)
	v_mfma_f32_16x16x32_bf16 v[60:63], v[108:111], v[228:231], v[60:63]
	v_exp_f32_e32 v212, v212
	v_exp_f32_e32 v213, v213
	v_exp_f32_e32 v214, v214
	v_exp_f32_e32 v215, v215
	v_add_f32_e32 v154, v212, v213
	v_exp_f32_e32 v216, v216
	v_mfma_f32_16x16x32_bf16 v[64:67], v[112:115], v[228:231], v[64:67]
	v_add_f32_e32 v155, v214, v215
	v_exp_f32_e32 v217, v217
	v_exp_f32_e32 v218, v218
	v_add_f32_e32 v154, v154, v216
	v_exp_f32_e32 v219, v219
	v_add_f32_e32 v155, v155, v217
	v_exp_f32_e32 v220, v220
	s_waitcnt lgkmcnt(4)
	v_mfma_f32_16x16x32_bf16 v[52:55], v[116:119], v[232:235], v[52:55]
	v_add_f32_e32 v154, v154, v218
	v_exp_f32_e32 v221, v221
	v_add_f32_e32 v155, v155, v219
	v_exp_f32_e32 v222, v222
	v_add_f32_e32 v154, v154, v220
	v_exp_f32_e32 v223, v223
	v_add_f32_e32 v155, v155, v221
	v_mfma_f32_16x16x32_bf16 v[56:59], v[120:123], v[232:235], v[56:59]
	v_exp_f32_e32 v224, v224
	v_add_f32_e32 v154, v154, v222
	v_exp_f32_e32 v225, v225
	v_add_f32_e32 v155, v155, v223
	v_exp_f32_e32 v226, v226
	v_add_f32_e32 v154, v154, v224
	s_waitcnt lgkmcnt(0)
	v_mfma_f32_16x16x32_bf16 v[60:63], v[124:127], v[232:235], v[60:63]
	v_exp_f32_e32 v227, v227
	v_add_f32_e32 v155, v155, v225
	v_add_f32_e32 v154, v154, v226
	v_add_f32_e32 v155, v155, v227
	v_add_f32_e32 v154, v154, v155
	v_add_f32_e32 v175, v175, v154
	v_cvt_pk_bf16_f32 v236, v212, v213
	v_mfma_f32_16x16x32_bf16 v[64:67], v[128:131], v[232:235], v[64:67]
	v_cvt_pk_bf16_f32 v237, v214, v215
	v_cvt_pk_bf16_f32 v238, v216, v217
	v_cvt_pk_bf16_f32 v239, v218, v219
	v_cvt_pk_bf16_f32 v240, v220, v221
	v_cvt_pk_bf16_f32 v241, v222, v223
	v_cvt_pk_bf16_f32 v242, v224, v225
	v_cvt_pk_bf16_f32 v243, v226, v227
	s_nop 0
	v_mfma_f32_16x16x32_bf16 v[36:39], v[100:103], v[236:239], v[36:39]
	v_mfma_f32_16x16x32_bf16 v[40:43], v[104:107], v[236:239], v[40:43]
	v_mfma_f32_16x16x32_bf16 v[44:47], v[108:111], v[236:239], v[44:47]
	v_mfma_f32_16x16x32_bf16 v[48:51], v[112:115], v[236:239], v[48:51]
	v_xor_b32_e32 v228, 0x80000000, v172
	v_mov_b32_e32 v229, v228
	v_mfma_f32_16x16x32_bf16 v[36:39], v[116:119], v[240:243], v[36:39]
	v_mfma_f32_16x16x32_bf16 v[40:43], v[120:123], v[240:243], v[40:43]
	v_mfma_f32_16x16x32_bf16 v[44:47], v[124:127], v[240:243], v[44:47]
	v_mfma_f32_16x16x32_bf16 v[48:51], v[128:131], v[240:243], v[48:51]
	v_mov_b32_e32 v230, v228
	v_mov_b32_e32 v231, v228
	v_xor_b32_e32 v236, 0x80000000, v173
	v_mov_b32_e32 v237, v236
	v_mov_b32_e32 v238, v236
	v_mov_b32_e32 v239, v236
	v_add_u32_e32 v211, s18, v168
	ds_read_b128 v[100:103], v211
	ds_read_b128 v[104:107], v211 offset:64
	ds_read_b128 v[108:111], v211 offset:2560
	ds_read_b128 v[112:115], v211 offset:2624
	ds_read_b128 v[116:119], v211 offset:5120
	ds_read_b128 v[120:123], v211 offset:5184
	ds_read_b128 v[124:127], v211 offset:7680
	ds_read_b128 v[128:131], v211 offset:7744
	s_setprio 1
	s_waitcnt lgkmcnt(7)
	v_mfma_f32_16x16x32_bf16 v[132:135], v[100:103], v[20:23], v[228:231]
	s_waitcnt lgkmcnt(6)
	v_mfma_f32_16x16x32_bf16 v[132:135], v[104:107], v[24:27], v[132:135]
	s_waitcnt lgkmcnt(4)
	v_mfma_f32_16x16x32_bf16 v[136:139], v[108:111], v[20:23], v[228:231]
	v_mfma_f32_16x16x32_bf16 v[136:139], v[112:115], v[24:27], v[136:139]
	s_waitcnt lgkmcnt(2)
	v_mfma_f32_16x16x32_bf16 v[140:143], v[116:119], v[20:23], v[228:231]
	v_mfma_f32_16x16x32_bf16 v[140:143], v[120:123], v[24:27], v[140:143]
	s_waitcnt lgkmcnt(0)
	v_mfma_f32_16x16x32_bf16 v[144:147], v[124:127], v[20:23], v[228:231]
	v_mfma_f32_16x16x32_bf16 v[144:147], v[128:131], v[24:27], v[144:147]
	v_mfma_f32_16x16x32_bf16 v[212:215], v[100:103], v[28:31], v[236:239]
	v_mfma_f32_16x16x32_bf16 v[212:215], v[104:107], v[32:35], v[212:215]
	v_max3_f32 v153, v132, v133, v134
	v_max3_f32 v154, v135, v136, v137
	v_mfma_f32_16x16x32_bf16 v[216:219], v[108:111], v[28:31], v[236:239]
	v_max3_f32 v155, v138, v139, v140
	v_max3_f32 v156, v141, v142, v143
	v_mfma_f32_16x16x32_bf16 v[216:219], v[112:115], v[32:35], v[216:219]
	s_nop 0
	v_max3_f32 v153, v153, v154, v144
	v_max3_f32 v155, v155, v156, v145
	v_max3_f32 v153, v153, v155, v146
	v_max_f32_e32 v153, v153, v147
	v_cmp_lt_f32_e32 vcc, 0x41000000, v153
	s_cbranch_vccnz .Lgqa_rare0_gb
.Lgqa_join0_gb:
	v_add_u32_e32 v208, s18, v169
	ds_read_b64 v[100:101], v208 offset:0
	ds_read_b64 v[102:103], v208 offset:32
	ds_read_b64 v[104:105], v208 offset:2304
	ds_read_b64 v[106:107], v208 offset:2336
	ds_read_b64 v[108:109], v208 offset:4608
	ds_read_b64 v[110:111], v208 offset:4640
	ds_read_b64 v[112:113], v208 offset:6912
	ds_read_b64 v[114:115], v208 offset:6944
	v_mfma_f32_16x16x32_bf16 v[220:223], v[116:119], v[28:31], v[236:239]
	v_exp_f32_e32 v132, v132
	v_exp_f32_e32 v133, v133
	v_exp_f32_e32 v134, v134
	v_exp_f32_e32 v135, v135
	v_add_f32_e32 v154, v132, v133
	v_exp_f32_e32 v136, v136
	v_add_f32_e32 v155, v134, v135
	v_exp_f32_e32 v137, v137
	v_exp_f32_e32 v138, v138
	v_add_f32_e32 v154, v154, v136
	v_mfma_f32_16x16x32_bf16 v[220:223], v[120:123], v[32:35], v[220:223]
	v_exp_f32_e32 v139, v139
	v_add_f32_e32 v155, v155, v137
	v_exp_f32_e32 v140, v140
	v_add_f32_e32 v154, v154, v138
	v_exp_f32_e32 v141, v141
	v_add_f32_e32 v155, v155, v139
	v_exp_f32_e32 v142, v142
	v_add_f32_e32 v154, v154, v140
	v_exp_f32_e32 v143, v143
	v_add_f32_e32 v155, v155, v141
	v_mfma_f32_16x16x32_bf16 v[224:227], v[124:127], v[28:31], v[236:239]
	v_exp_f32_e32 v144, v144
	v_add_f32_e32 v154, v154, v142
	v_exp_f32_e32 v145, v145
	v_add_f32_e32 v155, v155, v143
	v_exp_f32_e32 v146, v146
	v_add_f32_e32 v154, v154, v144
	v_exp_f32_e32 v147, v147
	v_add_f32_e32 v155, v155, v145
	v_add_f32_e32 v154, v154, v146
	v_add_f32_e32 v155, v155, v147
	v_mfma_f32_16x16x32_bf16 v[224:227], v[128:131], v[32:35], v[224:227]
	v_add_f32_e32 v154, v154, v155
	v_add_f32_e32 v174, v174, v154
	v_cvt_pk_bf16_f32 v228, v132, v133
	v_cvt_pk_bf16_f32 v229, v134, v135
	v_cvt_pk_bf16_f32 v230, v136, v137
	v_cvt_pk_bf16_f32 v231, v138, v139
	v_cvt_pk_bf16_f32 v232, v140, v141
	v_cvt_pk_bf16_f32 v233, v142, v143
	v_cvt_pk_bf16_f32 v234, v144, v145
	v_cvt_pk_bf16_f32 v235, v146, v147
	ds_read_b64 v[116:117], v208 offset:64
	ds_read_b64 v[118:119], v208 offset:96
	ds_read_b64 v[120:121], v208 offset:2368
	ds_read_b64 v[122:123], v208 offset:2400
	ds_read_b64 v[124:125], v208 offset:4672
	ds_read_b64 v[126:127], v208 offset:4704
	ds_read_b64 v[128:129], v208 offset:6976
	ds_read_b64 v[130:131], v208 offset:7008
	v_max3_f32 v153, v212, v213, v214
	v_max3_f32 v154, v215, v216, v217
	v_max3_f32 v155, v218, v219, v220
	v_max3_f32 v156, v221, v222, v223
	s_setprio 0
	s_waitcnt lgkmcnt(12)
	v_mfma_f32_16x16x32_bf16 v[72:75], v[100:103], v[228:231], v[72:75]
	v_max3_f32 v153, v153, v154, v224
	v_max3_f32 v155, v155, v156, v225
	v_mfma_f32_16x16x32_bf16 v[80:83], v[104:107], v[228:231], v[80:83]
	v_max3_f32 v153, v153, v155, v226
	v_max_f32_e32 v153, v153, v227
	v_cmp_lt_f32_e32 vcc, 0x41000000, v153
	s_cbranch_vccnz .Lgqa_rare1_gb

; template <int DK>
; DEVI void attn_tile(const char* kb, const char* vb, const bool first, const bf16x8 (&qf)[2][DK / 32], f32x4 (&o)[2][4],
;                     float (&mrun)[2], float (&lsum)[2], const int l15, const int quad) {
;     ...
; #pragma unroll
;   for (int ks = 0; ks < 4; ++ks)
; #pragma unroll
;     for (int kk = 0; kk < NKK; ++kk) {
;       bf16x8 kf = *reinterpret_cast<const bf16x8*>(kb + (ks * 16 + l15) * KSTR + (kk * 32 + quad * 8) * 2);
;       s[0][ks] = mfma16(kf, qf[0][kk], s[0][ks]);
;       s[1][ks] = mfma16(kf, qf[1][kk], s[1][ks]);
;     }
;   bf16x8 pf[2][2];
; #pragma unroll
;   for (int qt = 0; qt < 2; ++qt) {
;     float mx = fmaxf(fmaxf(s[qt][0][0], s[qt][0][1]), fmaxf(s[qt][0][2], s[qt][0][3]));
; #pragma unroll
;     for (int ks = 1; ks < 4; ++ks) mx = fmaxf(mx, fmaxf(fmaxf(s[qt][ks][0], s[qt][ks][1]), fmaxf(s[qt][ks][2], s[qt][ks][3])));
;     if (__any(first || (mx > 8.f))) {
;       float rm = fmaxf(mx, __shfl_xor(mx, 16));
;       rm = fmaxf(rm, __shfl_xor(rm, 32));
;       const float delta = first ? rm : fmaxf(rm, 0.f);
;       const float alpha = first ? 1.f : ex2(-delta);
;       mrun[qt] += delta;
;       lsum[qt] *= alpha;
; #pragma unroll
;       for (int ks = 0; ks < 4; ++ks)
; #pragma unroll
;         for (int j = 0; j < 4; ++j) s[qt][ks][j] -= delta;
; #pragma unroll
;       for (int dd = 0; dd < 4; ++dd)
; #pragma unroll
;         for (int j = 0; j < 4; ++j) o[qt][dd][j] *= alpha;
;     }
;     float ps = 0.f;
; #pragma unroll
;     for (int ks = 0; ks < 4; ++ks)
; #pragma unroll
;       for (int j = 0; j < 4; ++j) { float pv = ex2(s[qt][ks][j]); s[qt][ks][j] = pv; ps += pv; }
;     lsum[qt] += ps;
; #pragma unroll
;     for (int k2 = 0; k2 < 2; ++k2) {
;       u32x4 wv;
;       wv[0] = pack2(s[qt][2 * k2][0], s[qt][2 * k2][1]);
;       wv[1] = pack2(s[qt][2 * k2][2], s[qt][2 * k2][3]);
;       wv[2] = pack2(s[qt][2 * k2 + 1][0], s[qt][2 * k2 + 1][1]);
;       wv[3] = pack2(s[qt][2 * k2 + 1][2], s[qt][2 * k2 + 1][3]);
;       pf[qt][k2] = as_bf8(wv);
;     }
;   }
; #pragma unroll
;   for (int dd = 0; dd < 4; ++dd)
; #pragma unroll
;     for (int k2 = 0; k2 < 2; ++k2) {
;       u32x2 lo = *reinterpret_cast<const u32x2*>(vb + (dd * 16 + l15) * 144 + (k2 * 32 + quad * 4) * 2);
;       u32x2 hi = *reinterpret_cast<const u32x2*>(vb + (dd * 16 + l15) * 144 + (k2 * 32 + 16 + quad * 4) * 2);
.Lmla_loop_a:
	v_add_u32_e32 v148, s18, v209
	global_load_dwordx4 v[224:227], v167, s[12:13]
	global_load_dwordx4 v[228:231], v172, s[12:13]
	global_load_dwordx4 v[232:235], v173, s[12:13]
	ds_read_b128 v[60:63], v148
	ds_read_b128 v[64:67], v148 offset:64
	ds_read_b128 v[68:71], v148 offset:128
	global_load_dwordx4 v[168:171], v174, s[22:23]
	global_load_dwordx4 v[160:163], v175, s[22:23]
	ds_read_b128 v[72:75], v148 offset:3584
	ds_read_b128 v[76:79], v148 offset:3648
	ds_read_b128 v[80:83], v148 offset:3712
	ds_read_b128 v[84:87], v148 offset:7168
	ds_read_b128 v[88:91], v148 offset:7232
	ds_read_b128 v[92:95], v148 offset:7296
	ds_read_b128 v[96:99], v148 offset:10752
	ds_read_b128 v[100:103], v148 offset:10816
	ds_read_b128 v[104:107], v148 offset:10880
	s_add_i32 s96, s11, 2
	s_cmp_lt_i32 s96, s24
	s_cselect_b32 s96, 0x3000, 0
	s_cselect_b32 s17, 0x80, 0
	s_add_u32 s12, s12, s96
	s_addc_u32 s13, s13, 0
	s_add_u32 s22, s22, s17
	s_addc_u32 s23, s23, 0
	s_setprio 1
	s_waitcnt lgkmcnt(11)
	v_mfma_f32_16x16x32_bf16 v[108:111], v[60:63], v[4:7], v[204:207]
	s_waitcnt lgkmcnt(9)
	v_mfma_f32_16x16x32_bf16 v[108:111], v[64:67], v[8:11], v[108:111]
	v_mfma_f32_16x16x32_bf16 v[108:111], v[68:71], v[12:15], v[108:111]
	s_waitcnt lgkmcnt(6)
	v_mfma_f32_16x16x32_bf16 v[112:115], v[72:75], v[4:7], v[204:207]
	v_mfma_f32_16x16x32_bf16 v[112:115], v[76:79], v[8:11], v[112:115]
	v_mfma_f32_16x16x32_bf16 v[112:115], v[80:83], v[12:15], v[112:115]
	s_waitcnt lgkmcnt(3)
	v_mfma_f32_16x16x32_bf16 v[116:119], v[84:87], v[4:7], v[204:207]
	v_mfma_f32_16x16x32_bf16 v[116:119], v[88:91], v[8:11], v[116:119]
	v_mfma_f32_16x16x32_bf16 v[116:119], v[92:95], v[12:15], v[116:119]
	s_waitcnt lgkmcnt(0)
	v_mfma_f32_16x16x32_bf16 v[120:123], v[96:99], v[4:7], v[204:207]
	v_mfma_f32_16x16x32_bf16 v[120:123], v[100:103], v[8:11], v[120:123]
	v_mfma_f32_16x16x32_bf16 v[120:123], v[104:107], v[12:15], v[120:123]
	v_mfma_f32_16x16x32_bf16 v[124:127], v[60:63], v[16:19], v[212:215]
	v_mfma_f32_16x16x32_bf16 v[124:127], v[64:67], v[20:23], v[124:127]
	v_max3_f32 v150, v108, v109, v110
	v_max3_f32 v151, v111, v112, v113
	v_mfma_f32_16x16x32_bf16 v[124:127], v[68:71], v[24:27], v[124:127]
	v_max3_f32 v176, v114, v115, v116
	v_max3_f32 v177, v117, v118, v119
	v_mfma_f32_16x16x32_bf16 v[128:131], v[72:75], v[16:19], v[212:215]
	s_nop 0
	v_max3_f32 v150, v150, v151, v120
	v_max3_f32 v176, v176, v177, v121
	v_mfma_f32_16x16x32_bf16 v[128:131], v[76:79], v[20:23], v[128:131]
	v_max3_f32 v150, v150, v176, v122
	v_max_f32_e32 v150, v150, v123
	v_cmp_lt_f32_e32 vcc, 0x41000000, v150
	s_cbranch_vccnz .Lmla_rare0_a
.Lmla_join0_a:
	v_mfma_f32_16x16x32_bf16 v[128:131], v[80:83], v[24:27], v[128:131]
	v_add_u32_e32 v149, s18, v210
	ds_read_b64 v[60:61], v149 offset:0
	ds_read_b64 v[62:63], v149 offset:32
	ds_read_b64 v[64:65], v149 offset:2304
	ds_read_b64 v[66:67], v149 offset:2336
	ds_read_b64 v[68:69], v149 offset:4608
	ds_read_b64 v[70:71], v149 offset:4640
	ds_read_b64 v[72:73], v149 offset:6912
	ds_read_b64 v[74:75], v149 offset:6944
	v_exp_f32_e32 v108, v108
	v_exp_f32_e32 v109, v109
	v_exp_f32_e32 v110, v110
	v_exp_f32_e32 v111, v111
	v_add_f32_e32 v151, v108, v109
	v_mfma_f32_16x16x32_bf16 v[132:135], v[84:87], v[16:19], v[212:215]
	v_exp_f32_e32 v112, v112
	v_add_f32_e32 v176, v110, v111
	v_exp_f32_e32 v113, v113
	v_exp_f32_e32 v114, v114
	v_add_f32_e32 v151, v151, v112
	v_exp_f32_e32 v115, v115
	v_mfma_f32_16x16x32_bf16 v[132:135], v[88:91], v[20:23], v[132:135]
	v_add_f32_e32 v176, v176, v113
	v_exp_f32_e32 v116, v116
	v_add_f32_e32 v151, v151, v114
	v_exp_f32_e32 v117, v117
	v_add_f32_e32 v176, v176, v115
	v_exp_f32_e32 v118, v118
	ds_read_b64 v[76:77], v149 offset:64
	ds_read_b64 v[78:79], v149 offset:96
	ds_read_b64 v[80:81], v149 offset:2368
	ds_read_b64 v[82:83], v149 offset:2400
	ds_read_b64 v[84:85], v149 offset:4672
	ds_read_b64 v[86:87], v149 offset:4704
	ds_read_b64 v[88:89], v149 offset:6976
	ds_read_b64 v[90:91], v149 offset:7008
	v_mfma_f32_16x16x32_bf16 v[132:135], v[92:95], v[24:27], v[132:135]
	v_add_f32_e32 v151, v151, v116
	v_exp_f32_e32 v119, v119
	v_add_f32_e32 v176, v176, v117
	v_exp_f32_e32 v120, v120
	v_add_f32_e32 v151, v151, v118
	v_mfma_f32_16x16x32_bf16 v[136:139], v[96:99], v[16:19], v[212:215]
	v_exp_f32_e32 v121, v121
	v_add_f32_e32 v176, v176, v119
	v_exp_f32_e32 v122, v122
	v_add_f32_e32 v151, v151, v120
	v_exp_f32_e32 v123, v123
	v_add_f32_e32 v176, v176, v121
	v_mfma_f32_16x16x32_bf16 v[136:139], v[100:103], v[20:23], v[136:139]
	v_add_f32_e32 v151, v151, v122
	v_add_f32_e32 v176, v176, v123
	v_add_f32_e32 v151, v151, v176
	v_add_f32_e32 v166, v166, v151
	v_cvt_pk_bf16_f32 v140, v108, v109
	v_cvt_pk_bf16_f32 v141, v110, v111
	v_mfma_f32_16x16x32_bf16 v[136:139], v[104:107], v[24:27], v[136:139]
	v_cvt_pk_bf16_f32 v142, v112, v113
	v_cvt_pk_bf16_f32 v143, v114, v115
	v_cvt_pk_bf16_f32 v144, v116, v117
	v_cvt_pk_bf16_f32 v145, v118, v119
	v_cvt_pk_bf16_f32 v146, v120, v121
	v_cvt_pk_bf16_f32 v147, v122, v123
	s_setprio 0
	s_waitcnt lgkmcnt(12)
	v_mfma_f32_16x16x32_bf16 v[56:59], v[60:63], v[140:143], v[56:59]
	v_max3_f32 v150, v124, v125, v126
	v_max3_f32 v151, v127, v128, v129
	v_mfma_f32_16x16x32_bf16 v[48:51], v[64:67], v[140:143], v[48:51]
	v_max3_f32 v176, v130, v131, v132
	v_max3_f32 v177, v133, v134, v135
	v_max3_f32 v150, v150, v151, v136
	v_max3_f32 v176, v176, v177, v137
	s_waitcnt lgkmcnt(8)
	v_mfma_f32_16x16x32_bf16 v[44:47], v[68:71], v[140:143], v[44:47]
	v_max3_f32 v150, v150, v176, v138
	v_max_f32_e32 v150, v150, v139
	v_cmp_lt_f32_e32 vcc, 0x41000000, v150
	s_cbranch_vccnz .Lmla_rare1_a
